# attention row-max: 16-op v_max3 tree (two interleaved chains) behind a 13-state MFMA guard, on top of pipelined reads + setprio
# baseline (speedup 1.0000x reference)
.Lprio_1:
	s_nop 1
	s_nop 8
	s_nop 7
	s_nop 4
	v_max3_f32 v0, v50, v51, v52
	v_max3_f32 v97, v34, v35, v36
	v_max3_f32 v0, v0, v53, v54
	v_max3_f32 v97, v97, v37, v38
	v_max3_f32 v0, v0, v55, v56
	v_max3_f32 v97, v97, v39, v40
	v_max3_f32 v0, v0, v57, v58
	v_max3_f32 v97, v97, v41, v42
	v_max3_f32 v0, v0, v59, v60
	v_max3_f32 v97, v97, v43, v44
	v_max3_f32 v0, v0, v61, v62
	v_max3_f32 v97, v97, v45, v46
	v_max3_f32 v0, v0, v63, v64
	v_max3_f32 v97, v97, v47, v48
	v_max3_f32 v97, v97, v49, v65
	v_max_f32_e32 v0, v0, v97
	v_and_b32_e32 v104, 64, v221
	v_xor_b32_e32 v97, 32, v221
	v_add_u32_e32 v104, 64, v104
	v_cmp_lt_i32_e32 vcc, v97, v104
	s_nop 1
	v_cndmask_b32_e32 v97, v221, v97, vcc
	v_lshlrev_b32_e32 v104, 2, v97
	ds_bpermute_b32 v97, v104, v0
	s_waitcnt lgkmcnt(0)
	v_max3_f32 v97, v103, v0, v97
	v_sub_f32_e32 v0, v34, v97
	v_exp_f32_e32 v34, v0
	v_sub_f32_e32 v0, v50, v97
	v_exp_f32_e32 v50, v0
	v_sub_f32_e32 v0, v35, v97
	v_exp_f32_e32 v35, v0
	v_sub_f32_e32 v0, v51, v97
	v_exp_f32_e32 v51, v0
	v_sub_f32_e32 v36, v36, v97
	v_sub_f32_e32 v52, v52, v97
	v_exp_f32_e32 v36, v36
	v_exp_f32_e32 v52, v52
	v_sub_f32_e32 v0, v103, v97
	v_add_f32_e32 v103, v34, v50
	v_add_f32_e32 v103, 0, v103
	v_add_f32_e32 v105, v35, v51
	v_add_f32_e32 v103, v105, v103
	v_add_f32_e32 v105, v36, v52
	v_sub_f32_e32 v38, v38, v97
	v_sub_f32_e32 v37, v37, v97
	v_sub_f32_e32 v53, v53, v97
	v_add_f32_e32 v105, v105, v103
	v_exp_f32_e32 v103, v38
	v_sub_f32_e32 v38, v54, v97
	v_exp_f32_e32 v37, v37
	v_exp_f32_e32 v53, v53
	v_exp_f32_e32 v54, v38
	v_sub_f32_e32 v38, v39, v97
	v_exp_f32_e32 v39, v38
	v_sub_f32_e32 v38, v55, v97
	v_exp_f32_e32 v55, v38
	v_sub_f32_e32 v40, v40, v97
	v_sub_f32_e32 v56, v56, v97
	v_exp_f32_e32 v40, v40
	v_exp_f32_e32 v56, v56
	v_sub_f32_e32 v41, v41, v97
	v_sub_f32_e32 v57, v57, v97
	v_add_f32_e32 v106, v37, v53
	v_exp_f32_e32 v41, v41
	v_exp_f32_e32 v57, v57
	v_sub_f32_e32 v42, v42, v97
	v_sub_f32_e32 v58, v58, v97
	v_add_f32_e32 v38, v106, v105
	v_add_f32_e32 v105, v103, v54
	v_exp_f32_e32 v42, v42
	v_exp_f32_e32 v58, v58
	v_sub_f32_e32 v43, v43, v97
	v_sub_f32_e32 v59, v59, v97
	v_add_f32_e32 v38, v105, v38
	v_add_f32_e32 v105, v39, v55
	v_exp_f32_e32 v43, v43
	v_exp_f32_e32 v59, v59
	v_sub_f32_e32 v44, v44, v97
	v_sub_f32_e32 v60, v60, v97
	v_add_f32_e32 v38, v105, v38
	v_add_f32_e32 v105, v40, v56
	v_exp_f32_e32 v44, v44
	v_exp_f32_e32 v60, v60
	v_sub_f32_e32 v45, v45, v97
	v_sub_f32_e32 v61, v61, v97
	v_add_f32_e32 v38, v105, v38
	v_add_f32_e32 v105, v41, v57
	v_exp_f32_e32 v45, v45
	v_exp_f32_e32 v61, v61
	v_sub_f32_e32 v46, v46, v97
	v_sub_f32_e32 v62, v62, v97
	v_add_f32_e32 v38, v105, v38
	v_add_f32_e32 v105, v42, v58
	v_exp_f32_e32 v46, v46
	v_exp_f32_e32 v62, v62
	v_sub_f32_e32 v47, v47, v97
	v_sub_f32_e32 v63, v63, v97
	v_add_f32_e32 v38, v105, v38
	v_add_f32_e32 v105, v43, v59
	v_exp_f32_e32 v47, v47
	v_exp_f32_e32 v63, v63
	v_sub_f32_e32 v48, v48, v97
	v_sub_f32_e32 v64, v64, v97
	v_add_f32_e32 v38, v105, v38
	v_add_f32_e32 v105, v44, v60
	v_exp_f32_e32 v48, v48
	v_exp_f32_e32 v64, v64
	v_sub_f32_e32 v49, v49, v97
	v_sub_f32_e32 v65, v65, v97
	v_add_f32_e32 v38, v105, v38
	v_add_f32_e32 v105, v45, v61
	v_exp_f32_e32 v49, v49
	v_exp_f32_e32 v65, v65
	v_add_f32_e32 v38, v105, v38
	v_add_f32_e32 v105, v46, v62
	v_add_f32_e32 v38, v105, v38
	v_add_f32_e32 v105, v47, v63
	v_add_f32_e32 v38, v105, v38
	v_add_f32_e32 v105, v48, v64
	v_add_f32_e32 v38, v105, v38
	v_add_f32_e32 v105, v49, v65
	v_add_f32_e32 v38, v105, v38
	v_exp_f32_e32 v0, v0
	ds_bpermute_b32 v104, v104, v38
	v_cmp_neq_f32_e32 vcc, 1.0, v0
	s_cbranch_vccz .LBB0_342
	v_pk_mul_f32 v[32:33], v[32:33], v[0:1] op_sel_hi:[1,0]
	v_pk_mul_f32 v[30:31], v[30:31], v[0:1] op_sel_hi:[1,0]
	v_pk_mul_f32 v[28:29], v[28:29], v[0:1] op_sel_hi:[1,0]
	v_pk_mul_f32 v[26:27], v[26:27], v[0:1] op_sel_hi:[1,0]
	v_pk_mul_f32 v[24:25], v[24:25], v[0:1] op_sel_hi:[1,0]
	v_pk_mul_f32 v[22:23], v[22:23], v[0:1] op_sel_hi:[1,0]
	v_pk_mul_f32 v[20:21], v[20:21], v[0:1] op_sel_hi:[1,0]
	v_pk_mul_f32 v[18:19], v[18:19], v[0:1] op_sel_hi:[1,0]
	v_pk_mul_f32 v[16:17], v[16:17], v[0:1] op_sel_hi:[1,0]
	v_pk_mul_f32 v[14:15], v[14:15], v[0:1] op_sel_hi:[1,0]
	v_pk_mul_f32 v[12:13], v[12:13], v[0:1] op_sel_hi:[1,0]
	v_pk_mul_f32 v[10:11], v[10:11], v[0:1] op_sel_hi:[1,0]
	v_pk_mul_f32 v[8:9], v[8:9], v[0:1] op_sel_hi:[1,0]
	v_pk_mul_f32 v[6:7], v[6:7], v[0:1] op_sel_hi:[1,0]
	v_pk_mul_f32 v[4:5], v[4:5], v[0:1] op_sel_hi:[1,0]
	v_pk_mul_f32 v[2:3], v[2:3], v[0:1] op_sel_hi:[1,0]

.Lprio_4:
	s_nop 1
	s_nop 8
	s_nop 7
	s_nop 4
	v_max3_f32 v185, v82, v83, v84
	v_max3_f32 v187, v66, v67, v68
	v_max3_f32 v185, v185, v85, v86
	v_max3_f32 v187, v187, v69, v70
	v_max3_f32 v185, v185, v87, v88
	v_max3_f32 v187, v187, v71, v72
	v_max3_f32 v185, v185, v89, v90
	v_max3_f32 v187, v187, v73, v74
	v_max3_f32 v185, v185, v91, v92
	v_max3_f32 v187, v187, v75, v76
	v_max3_f32 v185, v185, v93, v94
	v_max3_f32 v187, v187, v77, v78
	v_max3_f32 v185, v185, v95, v96
	v_max3_f32 v187, v187, v79, v80
	v_max3_f32 v187, v187, v81, v97
	v_max_f32_e32 v185, v185, v187
	v_and_b32_e32 v188, 64, v221
	v_xor_b32_e32 v187, 32, v221
	v_add_u32_e32 v188, 64, v188
	v_cmp_lt_i32_e32 vcc, v187, v188
	s_nop 1
	v_cndmask_b32_e32 v187, v221, v187, vcc
	v_lshlrev_b32_e32 v193, 2, v187
	ds_bpermute_b32 v187, v193, v185
	s_waitcnt lgkmcnt(0)
	v_max3_f32 v185, v186, v185, v187
	v_sub_f32_e32 v66, v66, v185
	v_exp_f32_e32 v187, v66
	v_sub_f32_e32 v66, v82, v185
	v_exp_f32_e32 v188, v66
	v_sub_f32_e32 v66, v67, v185
	v_exp_f32_e32 v67, v66
	v_sub_f32_e32 v66, v83, v185
	v_exp_f32_e32 v83, v66
	v_sub_f32_e32 v68, v68, v185
	v_sub_f32_e32 v84, v84, v185
	v_exp_f32_e32 v68, v68
	v_exp_f32_e32 v84, v84
	v_add_f32_e32 v82, v187, v188
	v_sub_f32_e32 v69, v69, v185
	v_sub_f32_e32 v85, v85, v185
	v_sub_f32_e32 v66, v186, v185
	v_add_f32_e32 v82, 0, v82
	v_add_f32_e32 v186, v67, v83
	v_exp_f32_e32 v69, v69
	v_exp_f32_e32 v85, v85
	v_add_f32_e32 v82, v186, v82
	v_add_f32_e32 v186, v68, v84
	v_sub_f32_e32 v70, v70, v185
	v_add_f32_e32 v82, v186, v82
	v_exp_f32_e32 v186, v70
	v_sub_f32_e32 v70, v86, v185
	v_exp_f32_e32 v86, v70
	v_sub_f32_e32 v70, v71, v185
	v_add_f32_e32 v190, v69, v85
	v_exp_f32_e32 v189, v70
	v_sub_f32_e32 v70, v87, v185
	v_sub_f32_e32 v72, v72, v185
	v_exp_f32_e32 v87, v70
	v_add_f32_e32 v70, v190, v82
	v_exp_f32_e32 v190, v72
	v_sub_f32_e32 v72, v88, v185
	v_exp_f32_e32 v88, v72
	v_add_f32_e32 v71, v186, v86
	v_add_f32_e32 v70, v71, v70
	v_add_f32_e32 v71, v189, v87
	v_sub_f32_e32 v72, v73, v185
	v_exp_f32_e32 v73, v72
	v_sub_f32_e32 v72, v89, v185
	v_add_f32_e32 v70, v71, v70
	v_add_f32_e32 v71, v190, v88
	v_exp_f32_e32 v89, v72
	v_add_f32_e32 v82, v71, v70
	v_sub_f32_e32 v70, v74, v185
	v_sub_f32_e32 v71, v90, v185
	v_exp_f32_e32 v70, v70
	v_exp_f32_e32 v71, v71
	v_sub_f32_e32 v72, v75, v185
	v_sub_f32_e32 v74, v91, v185
	v_exp_f32_e32 v72, v72
	v_exp_f32_e32 v75, v74
	v_sub_f32_e32 v76, v76, v185
	v_sub_f32_e32 v90, v92, v185
	v_sub_f32_e32 v78, v78, v185
	v_exp_f32_e32 v76, v76
	v_exp_f32_e32 v90, v90
	v_sub_f32_e32 v77, v77, v185
	v_sub_f32_e32 v91, v93, v185
	v_exp_f32_e32 v92, v78
	v_sub_f32_e32 v78, v94, v185
	v_add_f32_e32 v191, v73, v89
	v_exp_f32_e32 v77, v77
	v_exp_f32_e32 v91, v91
	v_exp_f32_e32 v93, v78
	v_sub_f32_e32 v78, v79, v185
	v_sub_f32_e32 v79, v80, v185
	v_add_f32_e32 v74, v191, v82
	v_add_f32_e32 v82, v70, v71
	v_exp_f32_e32 v94, v78
	v_sub_f32_e32 v78, v95, v185
	v_exp_f32_e32 v191, v79
	v_sub_f32_e32 v79, v96, v185
	v_add_f32_e32 v74, v82, v74
	v_add_f32_e32 v82, v72, v75
	v_exp_f32_e32 v95, v78
	v_exp_f32_e32 v96, v79
	v_sub_f32_e32 v79, v81, v185
	v_add_f32_e32 v74, v82, v74
	v_add_f32_e32 v82, v76, v90
	v_exp_f32_e32 v192, v79
	v_sub_f32_e32 v79, v97, v185
	v_add_f32_e32 v74, v82, v74
	v_add_f32_e32 v82, v77, v91
	v_exp_f32_e32 v97, v79
	v_add_f32_e32 v74, v82, v74
	v_add_f32_e32 v78, v92, v93
	v_add_f32_e32 v74, v78, v74
	v_add_f32_e32 v78, v94, v95
	v_add_f32_e32 v74, v78, v74
	v_add_f32_e32 v78, v191, v96
	v_add_f32_e32 v74, v78, v74
	v_add_f32_e32 v78, v192, v97
	v_add_f32_e32 v74, v78, v74
	v_exp_f32_e32 v66, v66
	ds_bpermute_b32 v78, v193, v74
	v_cmp_neq_f32_e32 vcc, 1.0, v66
	s_cbranch_vccz .LBB0_354
	v_pk_mul_f32 v[64:65], v[64:65], v[66:67] op_sel_hi:[1,0]
	v_pk_mul_f32 v[62:63], v[62:63], v[66:67] op_sel_hi:[1,0]
	v_pk_mul_f32 v[60:61], v[60:61], v[66:67] op_sel_hi:[1,0]
	v_pk_mul_f32 v[58:59], v[58:59], v[66:67] op_sel_hi:[1,0]
	v_pk_mul_f32 v[56:57], v[56:57], v[66:67] op_sel_hi:[1,0]
	v_pk_mul_f32 v[54:55], v[54:55], v[66:67] op_sel_hi:[1,0]
	v_pk_mul_f32 v[52:53], v[52:53], v[66:67] op_sel_hi:[1,0]
	v_pk_mul_f32 v[50:51], v[50:51], v[66:67] op_sel_hi:[1,0]
	v_pk_mul_f32 v[48:49], v[48:49], v[66:67] op_sel_hi:[1,0]
	v_pk_mul_f32 v[46:47], v[46:47], v[66:67] op_sel_hi:[1,0]
	v_pk_mul_f32 v[44:45], v[44:45], v[66:67] op_sel_hi:[1,0]
	v_pk_mul_f32 v[42:43], v[42:43], v[66:67] op_sel_hi:[1,0]
	v_pk_mul_f32 v[40:41], v[40:41], v[66:67] op_sel_hi:[1,0]
	v_pk_mul_f32 v[38:39], v[38:39], v[66:67] op_sel_hi:[1,0]
	v_pk_mul_f32 v[36:37], v[36:37], v[66:67] op_sel_hi:[1,0]
	v_pk_mul_f32 v[34:35], v[34:35], v[66:67] op_sel_hi:[1,0]
	v_pk_mul_f32 v[32:33], v[32:33], v[66:67] op_sel_hi:[1,0]
	v_pk_mul_f32 v[30:31], v[30:31], v[66:67] op_sel_hi:[1,0]
	v_pk_mul_f32 v[28:29], v[28:29], v[66:67] op_sel_hi:[1,0]
	v_pk_mul_f32 v[26:27], v[26:27], v[66:67] op_sel_hi:[1,0]
	v_pk_mul_f32 v[24:25], v[24:25], v[66:67] op_sel_hi:[1,0]
	v_pk_mul_f32 v[22:23], v[22:23], v[66:67] op_sel_hi:[1,0]
	v_pk_mul_f32 v[20:21], v[20:21], v[66:67] op_sel_hi:[1,0]
	v_pk_mul_f32 v[18:19], v[18:19], v[66:67] op_sel_hi:[1,0]
	v_pk_mul_f32 v[16:17], v[16:17], v[66:67] op_sel_hi:[1,0]
	v_pk_mul_f32 v[14:15], v[14:15], v[66:67] op_sel_hi:[1,0]
	v_pk_mul_f32 v[12:13], v[12:13], v[66:67] op_sel_hi:[1,0]
	v_pk_mul_f32 v[10:11], v[10:11], v[66:67] op_sel_hi:[1,0]
	v_pk_mul_f32 v[8:9], v[8:9], v[66:67] op_sel_hi:[1,0]
	v_pk_mul_f32 v[6:7], v[6:7], v[66:67] op_sel_hi:[1,0]
	v_pk_mul_f32 v[4:5], v[4:5], v[66:67] op_sel_hi:[1,0]
	v_pk_mul_f32 v[2:3], v[2:3], v[66:67] op_sel_hi:[1,0]

.Lprio_7:
	s_nop 1
	s_nop 8
	s_nop 7
	s_nop 4
	v_max3_f32 v0, v50, v51, v52
	v_max3_f32 v96, v34, v35, v36
	v_max3_f32 v0, v0, v53, v54
	v_max3_f32 v96, v96, v37, v38
	v_max3_f32 v0, v0, v55, v56
	v_max3_f32 v96, v96, v39, v40
	v_max3_f32 v0, v0, v57, v58
	v_max3_f32 v96, v96, v41, v42
	v_max3_f32 v0, v0, v59, v60
	v_max3_f32 v96, v96, v43, v44
	v_max3_f32 v0, v0, v61, v62
	v_max3_f32 v96, v96, v45, v46
	v_max3_f32 v0, v0, v63, v64
	v_max3_f32 v96, v96, v47, v48
	v_max3_f32 v96, v96, v49, v65
	v_max_f32_e32 v0, v0, v96
	v_and_b32_e32 v102, 64, v221
	v_xor_b32_e32 v96, 32, v221
	v_add_u32_e32 v102, 64, v102
	v_cmp_lt_i32_e32 vcc, v96, v102
	s_nop 1
	v_cndmask_b32_e32 v96, v221, v96, vcc
	v_lshlrev_b32_e32 v102, 2, v96
	ds_bpermute_b32 v96, v102, v0
	s_waitcnt lgkmcnt(0)
	v_max3_f32 v96, v101, v0, v96
	v_sub_f32_e32 v0, v34, v96
	v_exp_f32_e32 v34, v0
	v_sub_f32_e32 v0, v50, v96
	v_exp_f32_e32 v50, v0
	v_sub_f32_e32 v0, v35, v96
	v_exp_f32_e32 v35, v0
	v_sub_f32_e32 v0, v51, v96
	v_exp_f32_e32 v51, v0
	v_sub_f32_e32 v36, v36, v96
	v_sub_f32_e32 v52, v52, v96
	v_exp_f32_e32 v36, v36
	v_exp_f32_e32 v52, v52
	v_sub_f32_e32 v0, v101, v96
	v_add_f32_e32 v101, v34, v50
	v_add_f32_e32 v101, 0, v101
	v_add_f32_e32 v103, v35, v51
	v_add_f32_e32 v101, v103, v101
	v_add_f32_e32 v103, v36, v52
	v_sub_f32_e32 v38, v38, v96
	v_sub_f32_e32 v37, v37, v96
	v_sub_f32_e32 v53, v53, v96
	v_add_f32_e32 v103, v103, v101
	v_exp_f32_e32 v101, v38
	v_sub_f32_e32 v38, v54, v96
	v_exp_f32_e32 v37, v37
	v_exp_f32_e32 v53, v53
	v_exp_f32_e32 v54, v38
	v_sub_f32_e32 v38, v39, v96
	v_exp_f32_e32 v39, v38
	v_sub_f32_e32 v38, v55, v96
	v_exp_f32_e32 v55, v38
	v_sub_f32_e32 v40, v40, v96
	v_sub_f32_e32 v56, v56, v96
	v_exp_f32_e32 v40, v40
	v_exp_f32_e32 v56, v56
	v_sub_f32_e32 v41, v41, v96
	v_sub_f32_e32 v57, v57, v96
	v_add_f32_e32 v104, v37, v53
	v_exp_f32_e32 v41, v41
	v_exp_f32_e32 v57, v57
	v_sub_f32_e32 v42, v42, v96
	v_sub_f32_e32 v58, v58, v96
	v_add_f32_e32 v38, v104, v103
	v_add_f32_e32 v103, v101, v54
	v_exp_f32_e32 v42, v42
	v_exp_f32_e32 v58, v58
	v_sub_f32_e32 v43, v43, v96
	v_sub_f32_e32 v59, v59, v96
	v_add_f32_e32 v38, v103, v38
	v_add_f32_e32 v103, v39, v55
	v_exp_f32_e32 v43, v43
	v_exp_f32_e32 v59, v59
	v_sub_f32_e32 v44, v44, v96
	v_sub_f32_e32 v60, v60, v96
	v_add_f32_e32 v38, v103, v38
	v_add_f32_e32 v103, v40, v56
	v_exp_f32_e32 v44, v44
	v_exp_f32_e32 v60, v60
	v_sub_f32_e32 v45, v45, v96
	v_sub_f32_e32 v61, v61, v96
	v_add_f32_e32 v38, v103, v38
	v_add_f32_e32 v103, v41, v57
	v_exp_f32_e32 v45, v45
	v_exp_f32_e32 v61, v61
	v_sub_f32_e32 v46, v46, v96
	v_sub_f32_e32 v62, v62, v96
	v_add_f32_e32 v38, v103, v38
	v_add_f32_e32 v103, v42, v58
	v_exp_f32_e32 v46, v46
	v_exp_f32_e32 v62, v62
	v_sub_f32_e32 v47, v47, v96
	v_sub_f32_e32 v63, v63, v96
	v_add_f32_e32 v38, v103, v38
	v_add_f32_e32 v103, v43, v59
	v_exp_f32_e32 v47, v47
	v_exp_f32_e32 v63, v63
	v_sub_f32_e32 v48, v48, v96
	v_sub_f32_e32 v64, v64, v96
	v_add_f32_e32 v38, v103, v38
	v_add_f32_e32 v103, v44, v60
	v_exp_f32_e32 v48, v48
	v_exp_f32_e32 v64, v64
	v_sub_f32_e32 v49, v49, v96
	v_sub_f32_e32 v65, v65, v96
	v_add_f32_e32 v38, v103, v38
	v_add_f32_e32 v103, v45, v61
	v_exp_f32_e32 v49, v49
	v_exp_f32_e32 v65, v65
	v_add_f32_e32 v38, v103, v38
	v_add_f32_e32 v103, v46, v62
	v_add_f32_e32 v38, v103, v38
	v_add_f32_e32 v103, v47, v63
	v_add_f32_e32 v38, v103, v38
	v_add_f32_e32 v103, v48, v64
	v_add_f32_e32 v38, v103, v38
	v_add_f32_e32 v103, v49, v65
	v_add_f32_e32 v38, v103, v38
	v_exp_f32_e32 v0, v0
	ds_bpermute_b32 v102, v102, v38
	v_cmp_neq_f32_e32 vcc, 1.0, v0
	s_cbranch_vccz .LBB0_371
	v_pk_mul_f32 v[32:33], v[32:33], v[0:1] op_sel_hi:[1,0]
	v_pk_mul_f32 v[30:31], v[30:31], v[0:1] op_sel_hi:[1,0]
	v_pk_mul_f32 v[28:29], v[28:29], v[0:1] op_sel_hi:[1,0]
	v_pk_mul_f32 v[26:27], v[26:27], v[0:1] op_sel_hi:[1,0]
	v_pk_mul_f32 v[24:25], v[24:25], v[0:1] op_sel_hi:[1,0]
	v_pk_mul_f32 v[22:23], v[22:23], v[0:1] op_sel_hi:[1,0]
	v_pk_mul_f32 v[20:21], v[20:21], v[0:1] op_sel_hi:[1,0]
	v_pk_mul_f32 v[18:19], v[18:19], v[0:1] op_sel_hi:[1,0]
	v_pk_mul_f32 v[16:17], v[16:17], v[0:1] op_sel_hi:[1,0]
	v_pk_mul_f32 v[14:15], v[14:15], v[0:1] op_sel_hi:[1,0]
	v_pk_mul_f32 v[12:13], v[12:13], v[0:1] op_sel_hi:[1,0]
	v_pk_mul_f32 v[10:11], v[10:11], v[0:1] op_sel_hi:[1,0]
	v_pk_mul_f32 v[8:9], v[8:9], v[0:1] op_sel_hi:[1,0]
	v_pk_mul_f32 v[6:7], v[6:7], v[0:1] op_sel_hi:[1,0]
	v_pk_mul_f32 v[4:5], v[4:5], v[0:1] op_sel_hi:[1,0]
	v_pk_mul_f32 v[2:3], v[2:3], v[0:1] op_sel_hi:[1,0]

.Lprio_13:
	s_nop 7
	s_nop 4
	v_max3_f32 v101, v50, v51, v52
	v_max3_f32 v102, v34, v35, v36
	v_max3_f32 v101, v101, v53, v54
	v_max3_f32 v102, v102, v37, v38
	v_max3_f32 v101, v101, v55, v56
	v_max3_f32 v102, v102, v39, v40
	v_max3_f32 v101, v101, v57, v58
	v_max3_f32 v102, v102, v41, v42
	v_max3_f32 v101, v101, v59, v60
	v_max3_f32 v102, v102, v43, v44
	v_max3_f32 v101, v101, v61, v62
	v_max3_f32 v102, v102, v45, v46
	v_max3_f32 v101, v101, v63, v64
	v_max3_f32 v102, v102, v47, v48
	v_max3_f32 v102, v102, v49, v65
	v_max_f32_e32 v101, v101, v102
	v_and_b32_e32 v103, 64, v221
	v_xor_b32_e32 v102, 32, v221
	v_add_u32_e32 v103, 64, v103
	v_cmp_lt_i32_e32 vcc, v102, v103
	s_mov_b32 s54, s2
	s_nop 0
	v_cndmask_b32_e32 v102, v221, v102, vcc
	v_lshlrev_b32_e32 v105, 2, v102
	ds_bpermute_b32 v102, v105, v101
	s_waitcnt lgkmcnt(0)
	v_max3_f32 v101, v0, v101, v102
	v_sub_f32_e32 v34, v34, v101
	v_sub_f32_e32 v50, v50, v101
	v_exp_f32_e32 v34, v34
	v_exp_f32_e32 v50, v50
	v_sub_f32_e32 v35, v35, v101
	v_sub_f32_e32 v51, v51, v101
	v_exp_f32_e32 v35, v35
	v_exp_f32_e32 v51, v51
	v_sub_f32_e32 v36, v36, v101
	v_sub_f32_e32 v52, v52, v101
	v_exp_f32_e32 v36, v36
	v_exp_f32_e32 v52, v52
	v_add_f32_e32 v102, v34, v50
	v_sub_f32_e32 v37, v37, v101
	v_sub_f32_e32 v53, v53, v101
	v_add_f32_e32 v102, 0, v102
	v_add_f32_e32 v103, v35, v51
	v_exp_f32_e32 v37, v37
	v_exp_f32_e32 v53, v53
	v_add_f32_e32 v102, v103, v102
	v_add_f32_e32 v103, v36, v52
	v_sub_f32_e32 v38, v38, v101
	v_add_f32_e32 v104, v103, v102
	v_exp_f32_e32 v102, v38
	v_sub_f32_e32 v38, v54, v101
	v_exp_f32_e32 v54, v38
	v_sub_f32_e32 v38, v39, v101
	v_add_f32_e32 v106, v37, v53
	v_exp_f32_e32 v103, v38
	v_sub_f32_e32 v38, v55, v101
	v_sub_f32_e32 v40, v40, v101
	v_exp_f32_e32 v55, v38
	v_add_f32_e32 v38, v106, v104
	v_exp_f32_e32 v104, v40
	v_sub_f32_e32 v40, v56, v101
	v_exp_f32_e32 v56, v40
	v_add_f32_e32 v39, v102, v54
	v_add_f32_e32 v38, v39, v38
	v_add_f32_e32 v39, v103, v55
	v_sub_f32_e32 v40, v41, v101
	v_exp_f32_e32 v41, v40
	v_sub_f32_e32 v40, v57, v101
	v_add_f32_e32 v38, v39, v38
	v_add_f32_e32 v39, v104, v56
	v_exp_f32_e32 v57, v40
	v_add_f32_e32 v106, v39, v38
	v_sub_f32_e32 v38, v42, v101
	v_sub_f32_e32 v39, v58, v101
	v_exp_f32_e32 v38, v38
	v_exp_f32_e32 v39, v39
	v_add_f32_e32 v107, v41, v57
	v_sub_f32_e32 v40, v43, v101
	v_sub_f32_e32 v42, v59, v101
	v_add_f32_e32 v43, v107, v106
	v_add_f32_e32 v58, v38, v39
	v_exp_f32_e32 v40, v40
	v_exp_f32_e32 v42, v42
	v_add_f32_e32 v59, v58, v43
	v_sub_f32_e32 v43, v44, v101
	v_sub_f32_e32 v44, v60, v101
	v_exp_f32_e32 v43, v43
	v_exp_f32_e32 v44, v44
	v_add_f32_e32 v106, v40, v42
	v_sub_f32_e32 v45, v45, v101
	v_sub_f32_e32 v58, v61, v101
	v_add_f32_e32 v59, v106, v59
	v_add_f32_e32 v60, v43, v44
	v_exp_f32_e32 v45, v45
	v_exp_f32_e32 v58, v58
	v_add_f32_e32 v61, v60, v59
	v_sub_f32_e32 v46, v46, v101
	v_sub_f32_e32 v59, v62, v101
	v_exp_f32_e32 v46, v46
	v_exp_f32_e32 v59, v59
	v_add_f32_e32 v106, v45, v58
	v_sub_f32_e32 v47, v47, v101
	v_sub_f32_e32 v60, v63, v101
	v_add_f32_e32 v61, v106, v61
	v_add_f32_e32 v62, v46, v59
	v_exp_f32_e32 v47, v47
	v_exp_f32_e32 v60, v60
	v_add_f32_e32 v63, v62, v61
	v_sub_f32_e32 v48, v48, v101
	v_sub_f32_e32 v61, v64, v101
	v_exp_f32_e32 v48, v48
	v_exp_f32_e32 v61, v61
	v_sub_f32_e32 v49, v49, v101
	v_sub_f32_e32 v62, v65, v101
	v_exp_f32_e32 v49, v49
	v_exp_f32_e32 v62, v62
	v_add_f32_e32 v106, v47, v60
	v_add_f32_e32 v63, v106, v63
	v_add_f32_e32 v64, v48, v61
	v_add_f32_e32 v63, v64, v63
	v_add_f32_e32 v64, v49, v62
	v_sub_f32_e32 v0, v0, v101
	v_add_f32_e32 v63, v64, v63
	v_exp_f32_e32 v0, v0
	ds_bpermute_b32 v64, v105, v63
	v_cmp_neq_f32_e32 vcc, 1.0, v0
	s_cbranch_vccz .LBB0_407
	v_pk_mul_f32 v[16:17], v[16:17], v[0:1] op_sel_hi:[1,0]
	v_pk_mul_f32 v[14:15], v[14:15], v[0:1] op_sel_hi:[1,0]
	v_pk_mul_f32 v[12:13], v[12:13], v[0:1] op_sel_hi:[1,0]
	v_pk_mul_f32 v[10:11], v[10:11], v[0:1] op_sel_hi:[1,0]
	v_pk_mul_f32 v[8:9], v[8:9], v[0:1] op_sel_hi:[1,0]
	v_pk_mul_f32 v[6:7], v[6:7], v[0:1] op_sel_hi:[1,0]
	v_pk_mul_f32 v[4:5], v[4:5], v[0:1] op_sel_hi:[1,0]
	v_pk_mul_f32 v[2:3], v[2:3], v[0:1] op_sel_hi:[1,0]
	v_pk_mul_f32 v[32:33], v[32:33], v[0:1] op_sel_hi:[1,0]
	v_pk_mul_f32 v[30:31], v[30:31], v[0:1] op_sel_hi:[1,0]
	v_pk_mul_f32 v[28:29], v[28:29], v[0:1] op_sel_hi:[1,0]
	v_pk_mul_f32 v[26:27], v[26:27], v[0:1] op_sel_hi:[1,0]
	v_pk_mul_f32 v[24:25], v[24:25], v[0:1] op_sel_hi:[1,0]
	v_pk_mul_f32 v[22:23], v[22:23], v[0:1] op_sel_hi:[1,0]
	v_pk_mul_f32 v[20:21], v[20:21], v[0:1] op_sel_hi:[1,0]
	v_pk_mul_f32 v[18:19], v[18:19], v[0:1] op_sel_hi:[1,0]

.Lprio_15:
	s_nop 10
	s_nop 7
	s_nop 4
	v_max3_f32 v66, v34, v35, v36
	v_max3_f32 v67, v50, v51, v52
	v_max3_f32 v66, v66, v37, v38
	v_max3_f32 v67, v67, v53, v54
	v_max3_f32 v66, v66, v39, v40
	v_max3_f32 v67, v67, v55, v56
	v_max3_f32 v66, v66, v41, v42
	v_max3_f32 v67, v67, v57, v58
	v_max3_f32 v66, v66, v43, v44
	v_max3_f32 v67, v67, v59, v60
	v_max3_f32 v66, v66, v45, v46
	v_max3_f32 v67, v67, v61, v62
	v_max3_f32 v66, v66, v47, v48
	v_max3_f32 v67, v67, v63, v64
	v_max3_f32 v67, v67, v65, v49
	v_max_f32_e32 v66, v66, v67
	v_and_b32_e32 v68, 64, v221
	v_xor_b32_e32 v67, 32, v221
	v_add_u32_e32 v68, 64, v68
	v_cmp_lt_i32_e32 vcc, v67, v68
	s_nop 1
	v_cndmask_b32_e32 v67, v221, v67, vcc
	v_lshlrev_b32_e32 v70, 2, v67
	ds_bpermute_b32 v67, v70, v66
	s_waitcnt lgkmcnt(0)
	v_max3_f32 v66, v0, v66, v67
	v_sub_f32_e32 v50, v50, v66
	v_sub_f32_e32 v34, v34, v66
	v_exp_f32_e32 v50, v50
	v_exp_f32_e32 v34, v34
	v_sub_f32_e32 v51, v51, v66
	v_sub_f32_e32 v35, v35, v66
	v_exp_f32_e32 v51, v51
	v_exp_f32_e32 v35, v35
	v_sub_f32_e32 v52, v52, v66
	v_sub_f32_e32 v36, v36, v66
	v_exp_f32_e32 v52, v52
	v_exp_f32_e32 v36, v36
	v_add_f32_e32 v67, v50, v34
	v_sub_f32_e32 v53, v53, v66
	v_sub_f32_e32 v37, v37, v66
	v_add_f32_e32 v67, 0, v67
	v_add_f32_e32 v68, v51, v35
	v_exp_f32_e32 v53, v53
	v_exp_f32_e32 v37, v37
	v_add_f32_e32 v67, v68, v67
	v_add_f32_e32 v68, v52, v36
	v_sub_f32_e32 v38, v38, v66
	v_add_f32_e32 v69, v68, v67
	v_sub_f32_e32 v54, v54, v66
	v_exp_f32_e32 v67, v38
	v_sub_f32_e32 v38, v55, v66
	v_exp_f32_e32 v54, v54
	v_exp_f32_e32 v55, v38
	v_sub_f32_e32 v38, v39, v66
	v_add_f32_e32 v71, v53, v37
	v_exp_f32_e32 v68, v38
	v_sub_f32_e32 v56, v56, v66
	v_sub_f32_e32 v40, v40, v66
	v_add_f32_e32 v38, v71, v69
	v_exp_f32_e32 v56, v56
	v_exp_f32_e32 v69, v40
	v_add_f32_e32 v39, v54, v67
	v_add_f32_e32 v38, v39, v38
	v_add_f32_e32 v39, v55, v68
	v_sub_f32_e32 v40, v57, v66
	v_exp_f32_e32 v57, v40
	v_sub_f32_e32 v40, v41, v66
	v_add_f32_e32 v38, v39, v38
	v_add_f32_e32 v39, v56, v69
	v_exp_f32_e32 v41, v40
	v_add_f32_e32 v71, v39, v38
	v_sub_f32_e32 v38, v58, v66
	v_sub_f32_e32 v39, v42, v66
	v_exp_f32_e32 v38, v38
	v_exp_f32_e32 v39, v39
	v_add_f32_e32 v72, v57, v41
	v_sub_f32_e32 v40, v59, v66
	v_sub_f32_e32 v42, v43, v66
	v_add_f32_e32 v43, v72, v71
	v_add_f32_e32 v58, v38, v39
	v_exp_f32_e32 v40, v40
	v_exp_f32_e32 v42, v42
	v_add_f32_e32 v59, v58, v43
	v_sub_f32_e32 v43, v60, v66
	v_sub_f32_e32 v44, v44, v66
	v_exp_f32_e32 v43, v43
	v_exp_f32_e32 v44, v44
	v_add_f32_e32 v71, v40, v42
	v_sub_f32_e32 v58, v61, v66
	v_sub_f32_e32 v45, v45, v66
	v_add_f32_e32 v59, v71, v59
	v_add_f32_e32 v60, v43, v44
	v_exp_f32_e32 v58, v58
	v_exp_f32_e32 v45, v45
	v_add_f32_e32 v61, v60, v59
	v_sub_f32_e32 v59, v62, v66
	v_sub_f32_e32 v46, v46, v66
	v_exp_f32_e32 v59, v59
	v_exp_f32_e32 v46, v46
	v_add_f32_e32 v71, v58, v45
	v_sub_f32_e32 v60, v63, v66
	v_sub_f32_e32 v47, v47, v66
	v_add_f32_e32 v61, v71, v61
	v_add_f32_e32 v62, v59, v46
	v_exp_f32_e32 v60, v60
	v_exp_f32_e32 v47, v47
	v_add_f32_e32 v63, v62, v61
	v_sub_f32_e32 v61, v64, v66
	v_sub_f32_e32 v48, v48, v66
	v_exp_f32_e32 v61, v61
	v_exp_f32_e32 v48, v48
	v_sub_f32_e32 v62, v65, v66
	v_sub_f32_e32 v49, v49, v66
	v_exp_f32_e32 v62, v62
	v_exp_f32_e32 v49, v49
	v_add_f32_e32 v71, v60, v47
	v_add_f32_e32 v63, v71, v63
	v_add_f32_e32 v64, v61, v48
	v_add_f32_e32 v63, v64, v63
	v_add_f32_e32 v64, v62, v49
	v_sub_f32_e32 v0, v0, v66
	v_add_f32_e32 v63, v64, v63
	v_exp_f32_e32 v0, v0
	ds_bpermute_b32 v64, v70, v63
	v_cmp_neq_f32_e32 vcc, 1.0, v0
	s_cbranch_vccz .LBB0_423
	v_pk_mul_f32 v[16:17], v[16:17], v[0:1] op_sel_hi:[1,0]
	v_pk_mul_f32 v[14:15], v[14:15], v[0:1] op_sel_hi:[1,0]
	v_pk_mul_f32 v[12:13], v[12:13], v[0:1] op_sel_hi:[1,0]
	v_pk_mul_f32 v[10:11], v[10:11], v[0:1] op_sel_hi:[1,0]
	v_pk_mul_f32 v[8:9], v[8:9], v[0:1] op_sel_hi:[1,0]
	v_pk_mul_f32 v[6:7], v[6:7], v[0:1] op_sel_hi:[1,0]
	v_pk_mul_f32 v[4:5], v[4:5], v[0:1] op_sel_hi:[1,0]
	v_pk_mul_f32 v[2:3], v[2:3], v[0:1] op_sel_hi:[1,0]
	v_pk_mul_f32 v[32:33], v[32:33], v[0:1] op_sel_hi:[1,0]
	v_pk_mul_f32 v[30:31], v[30:31], v[0:1] op_sel_hi:[1,0]
	v_pk_mul_f32 v[28:29], v[28:29], v[0:1] op_sel_hi:[1,0]
	v_pk_mul_f32 v[26:27], v[26:27], v[0:1] op_sel_hi:[1,0]
	v_pk_mul_f32 v[24:25], v[24:25], v[0:1] op_sel_hi:[1,0]
	v_pk_mul_f32 v[22:23], v[22:23], v[0:1] op_sel_hi:[1,0]
	v_pk_mul_f32 v[20:21], v[20:21], v[0:1] op_sel_hi:[1,0]
	v_pk_mul_f32 v[18:19], v[18:19], v[0:1] op_sel_hi:[1,0]
	s_branch .LBB0_423

.Lprio_10:
	s_nop 1
	s_nop 8
	s_nop 7
	s_nop 4
	v_max3_f32 v187, v82, v83, v84
	v_max3_f32 v189, v66, v67, v68
	v_max3_f32 v187, v187, v85, v86
	v_max3_f32 v189, v189, v69, v70
	v_max3_f32 v187, v187, v87, v88
	v_max3_f32 v189, v189, v71, v72
	v_max3_f32 v187, v187, v89, v90
	v_max3_f32 v189, v189, v73, v74
	v_max3_f32 v187, v187, v91, v92
	v_max3_f32 v189, v189, v75, v76
	v_max3_f32 v187, v187, v93, v94
	v_max3_f32 v189, v189, v77, v78
	v_max3_f32 v187, v187, v95, v96
	v_max3_f32 v189, v189, v79, v80
	v_max3_f32 v189, v189, v81, v97
	v_max_f32_e32 v187, v187, v189
	v_and_b32_e32 v190, 64, v221
	v_xor_b32_e32 v189, 32, v221
	v_add_u32_e32 v190, 64, v190
	v_cmp_lt_i32_e32 vcc, v189, v190
	s_nop 1
	v_cndmask_b32_e32 v189, v221, v189, vcc
	v_lshlrev_b32_e32 v195, 2, v189
	ds_bpermute_b32 v189, v195, v187
	s_waitcnt lgkmcnt(0)
	v_max3_f32 v187, v188, v187, v189
	v_sub_f32_e32 v66, v66, v187
	v_exp_f32_e32 v189, v66
	v_sub_f32_e32 v66, v82, v187
	v_exp_f32_e32 v190, v66
	v_sub_f32_e32 v66, v67, v187
	v_exp_f32_e32 v67, v66
	v_sub_f32_e32 v66, v83, v187
	v_exp_f32_e32 v83, v66
	v_sub_f32_e32 v68, v68, v187
	v_sub_f32_e32 v84, v84, v187
	v_exp_f32_e32 v68, v68
	v_exp_f32_e32 v84, v84
	v_add_f32_e32 v82, v189, v190
	v_sub_f32_e32 v69, v69, v187
	v_sub_f32_e32 v85, v85, v187
	v_sub_f32_e32 v66, v188, v187
	v_add_f32_e32 v82, 0, v82
	v_add_f32_e32 v188, v67, v83
	v_exp_f32_e32 v69, v69
	v_exp_f32_e32 v85, v85
	v_add_f32_e32 v82, v188, v82
	v_add_f32_e32 v188, v68, v84
	v_sub_f32_e32 v70, v70, v187
	v_add_f32_e32 v82, v188, v82
	v_exp_f32_e32 v188, v70
	v_sub_f32_e32 v70, v86, v187
	v_exp_f32_e32 v86, v70
	v_sub_f32_e32 v70, v71, v187
	v_add_f32_e32 v192, v69, v85
	v_exp_f32_e32 v191, v70
	v_sub_f32_e32 v70, v87, v187
	v_sub_f32_e32 v72, v72, v187
	v_exp_f32_e32 v87, v70
	v_add_f32_e32 v70, v192, v82
	v_exp_f32_e32 v192, v72
	v_sub_f32_e32 v72, v88, v187
	v_exp_f32_e32 v88, v72
	v_add_f32_e32 v71, v188, v86
	v_add_f32_e32 v70, v71, v70
	v_add_f32_e32 v71, v191, v87
	v_sub_f32_e32 v72, v73, v187
	v_exp_f32_e32 v73, v72
	v_sub_f32_e32 v72, v89, v187
	v_add_f32_e32 v70, v71, v70
	v_add_f32_e32 v71, v192, v88
	v_exp_f32_e32 v89, v72
	v_add_f32_e32 v82, v71, v70
	v_sub_f32_e32 v70, v74, v187
	v_sub_f32_e32 v71, v90, v187
	v_exp_f32_e32 v70, v70
	v_exp_f32_e32 v71, v71
	v_sub_f32_e32 v72, v75, v187
	v_sub_f32_e32 v74, v91, v187
	v_exp_f32_e32 v72, v72
	v_exp_f32_e32 v75, v74
	v_sub_f32_e32 v76, v76, v187
	v_sub_f32_e32 v90, v92, v187
	v_sub_f32_e32 v78, v78, v187
	v_exp_f32_e32 v76, v76
	v_exp_f32_e32 v90, v90
	v_sub_f32_e32 v77, v77, v187
	v_sub_f32_e32 v91, v93, v187
	v_exp_f32_e32 v92, v78
	v_sub_f32_e32 v78, v94, v187
	v_add_f32_e32 v193, v73, v89
	v_exp_f32_e32 v77, v77
	v_exp_f32_e32 v91, v91
	v_exp_f32_e32 v93, v78
	v_sub_f32_e32 v78, v79, v187
	v_sub_f32_e32 v79, v80, v187
	v_add_f32_e32 v74, v193, v82
	v_add_f32_e32 v82, v70, v71
	v_exp_f32_e32 v94, v78
	v_sub_f32_e32 v78, v95, v187
	v_exp_f32_e32 v193, v79
	v_sub_f32_e32 v79, v96, v187
	v_add_f32_e32 v74, v82, v74
	v_add_f32_e32 v82, v72, v75
	v_exp_f32_e32 v95, v78
	v_exp_f32_e32 v96, v79
	v_sub_f32_e32 v79, v81, v187
	v_add_f32_e32 v74, v82, v74
	v_add_f32_e32 v82, v76, v90
	v_exp_f32_e32 v194, v79
	v_sub_f32_e32 v79, v97, v187
	v_add_f32_e32 v74, v82, v74
	v_add_f32_e32 v82, v77, v91
	v_exp_f32_e32 v97, v79
	v_add_f32_e32 v74, v82, v74
	v_add_f32_e32 v78, v92, v93
	v_add_f32_e32 v74, v78, v74
	v_add_f32_e32 v78, v94, v95
	v_add_f32_e32 v74, v78, v74
	v_add_f32_e32 v78, v193, v96
	v_add_f32_e32 v74, v78, v74
	v_add_f32_e32 v78, v194, v97
	v_add_f32_e32 v74, v78, v74
	v_exp_f32_e32 v66, v66
	ds_bpermute_b32 v78, v195, v74
	v_cmp_neq_f32_e32 vcc, 1.0, v66
	s_cbranch_vccz .LBB0_520
	v_pk_mul_f32 v[64:65], v[64:65], v[66:67] op_sel_hi:[1,0]
	v_pk_mul_f32 v[62:63], v[62:63], v[66:67] op_sel_hi:[1,0]
	v_pk_mul_f32 v[60:61], v[60:61], v[66:67] op_sel_hi:[1,0]
	v_pk_mul_f32 v[58:59], v[58:59], v[66:67] op_sel_hi:[1,0]
	v_pk_mul_f32 v[56:57], v[56:57], v[66:67] op_sel_hi:[1,0]
	v_pk_mul_f32 v[54:55], v[54:55], v[66:67] op_sel_hi:[1,0]
	v_pk_mul_f32 v[52:53], v[52:53], v[66:67] op_sel_hi:[1,0]
	v_pk_mul_f32 v[50:51], v[50:51], v[66:67] op_sel_hi:[1,0]
	v_pk_mul_f32 v[48:49], v[48:49], v[66:67] op_sel_hi:[1,0]
	v_pk_mul_f32 v[46:47], v[46:47], v[66:67] op_sel_hi:[1,0]
	v_pk_mul_f32 v[44:45], v[44:45], v[66:67] op_sel_hi:[1,0]
	v_pk_mul_f32 v[42:43], v[42:43], v[66:67] op_sel_hi:[1,0]
	v_pk_mul_f32 v[40:41], v[40:41], v[66:67] op_sel_hi:[1,0]
	v_pk_mul_f32 v[38:39], v[38:39], v[66:67] op_sel_hi:[1,0]
	v_pk_mul_f32 v[36:37], v[36:37], v[66:67] op_sel_hi:[1,0]
	v_pk_mul_f32 v[34:35], v[34:35], v[66:67] op_sel_hi:[1,0]
	v_pk_mul_f32 v[32:33], v[32:33], v[66:67] op_sel_hi:[1,0]
	v_pk_mul_f32 v[30:31], v[30:31], v[66:67] op_sel_hi:[1,0]
	v_pk_mul_f32 v[28:29], v[28:29], v[66:67] op_sel_hi:[1,0]
	v_pk_mul_f32 v[26:27], v[26:27], v[66:67] op_sel_hi:[1,0]
	v_pk_mul_f32 v[24:25], v[24:25], v[66:67] op_sel_hi:[1,0]
	v_pk_mul_f32 v[22:23], v[22:23], v[66:67] op_sel_hi:[1,0]
	v_pk_mul_f32 v[20:21], v[20:21], v[66:67] op_sel_hi:[1,0]
	v_pk_mul_f32 v[18:19], v[18:19], v[66:67] op_sel_hi:[1,0]
	v_pk_mul_f32 v[16:17], v[16:17], v[66:67] op_sel_hi:[1,0]
	v_pk_mul_f32 v[14:15], v[14:15], v[66:67] op_sel_hi:[1,0]
	v_pk_mul_f32 v[12:13], v[12:13], v[66:67] op_sel_hi:[1,0]
	v_pk_mul_f32 v[10:11], v[10:11], v[66:67] op_sel_hi:[1,0]
	v_pk_mul_f32 v[8:9], v[8:9], v[66:67] op_sel_hi:[1,0]
	v_pk_mul_f32 v[6:7], v[6:7], v[66:67] op_sel_hi:[1,0]
	v_pk_mul_f32 v[4:5], v[4:5], v[66:67] op_sel_hi:[1,0]
	v_pk_mul_f32 v[2:3], v[2:3], v[66:67] op_sel_hi:[1,0]
